# attention epilogue: O tile transposed through wave-private LDS, 8 full-row dwordx4 stores instead of 64 short stores
# baseline (speedup 1.0000x reference)
.LBB0_485:
	s_or_b64 exec, exec, s[4:5]
	s_waitcnt lgkmcnt(0)
	v_add_u32_e32 v82, v181, v178
	ds_read_b128 v[64:67], v82
	ds_read_b128 v[68:71], v82 offset:32
	ds_read_b128 v[72:75], v82 offset:64
	ds_read_b128 v[76:79], v82 offset:96
	s_lshl_b64 s[2:3], s[6:7], 1
	s_add_u32 s4, s78, s2
	s_addc_u32 s5, s79, s3
	s_lshl_b64 s[2:3], s[66:67], 1
	s_add_u32 s2, s4, s2
	s_addc_u32 s3, s5, s3
	v_readfirstlane_b32 s4, v214
	v_and_b32_e32 v83, 0x1c0, v214
	v_lshlrev_b32_e32 v83, 5, v83
	v_add_u32_e32 v83, 0x24000, v83
	v_and_b32_e32 v80, 31, v214
	v_lshlrev_b32_e32 v80, 1, v80
	v_lshl_add_u32 v80, v190, 10, v80
	v_add_u32_e32 v80, v80, v83
	v_bfe_u32 v81, v214, 4, 2
	v_and_b32_e32 v82, 15, v214
	v_lshlrev_b32_e32 v82, 4, v82
	v_lshl_add_u32 v96, v81, 11, v82
	v_lshl_add_u32 v81, v81, 8, v82
	v_add_u32_e32 v81, v81, v83
	s_lshr_b32 s4, s4, 6
	s_lshl_b32 s4, s4, 16
	s_add_u32 s2, s2, s4
	s_addc_u32 s3, s3, 0
	s_add_u32 s4, s2, 0x2000
	s_addc_u32 s5, s3, 0
	s_waitcnt lgkmcnt(0)
	v_rcp_f32_e32 v64, v64
	v_rcp_f32_e32 v65, v65
	v_rcp_f32_e32 v66, v66
	v_rcp_f32_e32 v67, v67
	v_rcp_f32_e32 v68, v68
	v_rcp_f32_e32 v69, v69
	v_rcp_f32_e32 v70, v70
	v_rcp_f32_e32 v71, v71
	v_rcp_f32_e32 v72, v72
	v_rcp_f32_e32 v73, v73
	v_rcp_f32_e32 v74, v74
	v_rcp_f32_e32 v75, v75
	v_rcp_f32_e32 v76, v76
	v_rcp_f32_e32 v77, v77
	v_rcp_f32_e32 v78, v78
	v_rcp_f32_e32 v79, v79
	s_nop 1
	v_mul_f32_e32 v0, v0, v64
	v_mul_f32_e32 v1, v1, v65
	v_mul_f32_e32 v2, v2, v66
	v_mul_f32_e32 v3, v3, v67
	v_mul_f32_e32 v48, v48, v64
	v_mul_f32_e32 v49, v49, v65
	v_mul_f32_e32 v50, v50, v66
	v_mul_f32_e32 v51, v51, v67
	v_mul_f32_e32 v32, v32, v64
	v_mul_f32_e32 v33, v33, v65
	v_mul_f32_e32 v34, v34, v66
	v_mul_f32_e32 v35, v35, v67
	v_mul_f32_e32 v16, v16, v64
	v_mul_f32_e32 v17, v17, v65
	v_mul_f32_e32 v18, v18, v66
	v_mul_f32_e32 v19, v19, v67
	v_cvt_pk_bf16_f32 v0, v0, v1
	v_cvt_pk_bf16_f32 v1, v2, v3
	v_cvt_pk_bf16_f32 v48, v48, v49
	v_cvt_pk_bf16_f32 v49, v50, v51
	v_cvt_pk_bf16_f32 v32, v32, v33
	v_cvt_pk_bf16_f32 v33, v34, v35
	v_cvt_pk_bf16_f32 v16, v16, v17
	v_cvt_pk_bf16_f32 v17, v18, v19
	ds_write_b16 v80, v0
	ds_write_b16_d16_hi v80, v0 offset:256
	ds_write_b16 v80, v1 offset:512
	ds_write_b16_d16_hi v80, v1 offset:768
	ds_write_b16 v80, v48 offset:64
	ds_write_b16_d16_hi v80, v48 offset:320
	ds_write_b16 v80, v49 offset:576
	ds_write_b16_d16_hi v80, v49 offset:832
	ds_write_b16 v80, v32 offset:128
	ds_write_b16_d16_hi v80, v32 offset:384
	ds_write_b16 v80, v33 offset:640
	ds_write_b16_d16_hi v80, v33 offset:896
	ds_write_b16 v80, v16 offset:192
	ds_write_b16_d16_hi v80, v16 offset:448
	ds_write_b16 v80, v17 offset:704
	ds_write_b16_d16_hi v80, v17 offset:960
	ds_read_b128 v[0:3], v81
	ds_read_b128 v[48:51], v81 offset:1024
	v_mul_f32_e32 v4, v4, v68
	v_mul_f32_e32 v5, v5, v69
	v_mul_f32_e32 v6, v6, v70
	v_mul_f32_e32 v7, v7, v71
	v_mul_f32_e32 v52, v52, v68
	v_mul_f32_e32 v53, v53, v69
	v_mul_f32_e32 v54, v54, v70
	v_mul_f32_e32 v55, v55, v71
	v_mul_f32_e32 v36, v36, v68
	v_mul_f32_e32 v37, v37, v69
	v_mul_f32_e32 v38, v38, v70
	v_mul_f32_e32 v39, v39, v71
	v_mul_f32_e32 v20, v20, v68
	v_mul_f32_e32 v21, v21, v69
	v_mul_f32_e32 v22, v22, v70
	v_mul_f32_e32 v23, v23, v71
	v_cvt_pk_bf16_f32 v4, v4, v5
	v_cvt_pk_bf16_f32 v5, v6, v7
	v_cvt_pk_bf16_f32 v52, v52, v53
	v_cvt_pk_bf16_f32 v53, v54, v55
	v_cvt_pk_bf16_f32 v36, v36, v37
	v_cvt_pk_bf16_f32 v37, v38, v39
	v_cvt_pk_bf16_f32 v20, v20, v21
	v_cvt_pk_bf16_f32 v21, v22, v23
	s_waitcnt lgkmcnt(0)
	global_store_dwordx4 v96, v[0:3], s[2:3]
	global_store_dwordx4 v96, v[48:51], s[4:5]
	s_add_u32 s2, s2, 0x4000
	s_addc_u32 s3, s3, 0
	s_add_u32 s4, s4, 0x4000
	s_addc_u32 s5, s5, 0
	ds_write_b16 v80, v4
	ds_write_b16_d16_hi v80, v4 offset:256
	ds_write_b16 v80, v5 offset:512
	ds_write_b16_d16_hi v80, v5 offset:768
	ds_write_b16 v80, v52 offset:64
	ds_write_b16_d16_hi v80, v52 offset:320
	ds_write_b16 v80, v53 offset:576
	ds_write_b16_d16_hi v80, v53 offset:832
	ds_write_b16 v80, v36 offset:128
	ds_write_b16_d16_hi v80, v36 offset:384
	ds_write_b16 v80, v37 offset:640
	ds_write_b16_d16_hi v80, v37 offset:896
	ds_write_b16 v80, v20 offset:192
	ds_write_b16_d16_hi v80, v20 offset:448
	ds_write_b16 v80, v21 offset:704
	ds_write_b16_d16_hi v80, v21 offset:960
	ds_read_b128 v[4:7], v81
	ds_read_b128 v[52:55], v81 offset:1024
	v_mul_f32_e32 v8, v8, v72
	v_mul_f32_e32 v9, v9, v73
	v_mul_f32_e32 v10, v10, v74
	v_mul_f32_e32 v11, v11, v75
	v_mul_f32_e32 v56, v56, v72
	v_mul_f32_e32 v57, v57, v73
	v_mul_f32_e32 v58, v58, v74
	v_mul_f32_e32 v59, v59, v75
	v_mul_f32_e32 v40, v40, v72
	v_mul_f32_e32 v41, v41, v73
	v_mul_f32_e32 v42, v42, v74
	v_mul_f32_e32 v43, v43, v75
	v_mul_f32_e32 v24, v24, v72
	v_mul_f32_e32 v25, v25, v73
	v_mul_f32_e32 v26, v26, v74
	v_mul_f32_e32 v27, v27, v75
	v_cvt_pk_bf16_f32 v8, v8, v9
	v_cvt_pk_bf16_f32 v9, v10, v11
	v_cvt_pk_bf16_f32 v56, v56, v57
	v_cvt_pk_bf16_f32 v57, v58, v59
	v_cvt_pk_bf16_f32 v40, v40, v41
	v_cvt_pk_bf16_f32 v41, v42, v43
	v_cvt_pk_bf16_f32 v24, v24, v25
	v_cvt_pk_bf16_f32 v25, v26, v27
	s_waitcnt lgkmcnt(0)
	global_store_dwordx4 v96, v[4:7], s[2:3]
	global_store_dwordx4 v96, v[52:55], s[4:5]
	s_add_u32 s2, s2, 0x4000
	s_addc_u32 s3, s3, 0
	s_add_u32 s4, s4, 0x4000
	s_addc_u32 s5, s5, 0
	ds_write_b16 v80, v8
	ds_write_b16_d16_hi v80, v8 offset:256
	ds_write_b16 v80, v9 offset:512
	ds_write_b16_d16_hi v80, v9 offset:768
	ds_write_b16 v80, v56 offset:64
	ds_write_b16_d16_hi v80, v56 offset:320
	ds_write_b16 v80, v57 offset:576
	ds_write_b16_d16_hi v80, v57 offset:832
	ds_write_b16 v80, v40 offset:128
	ds_write_b16_d16_hi v80, v40 offset:384
	ds_write_b16 v80, v41 offset:640
	ds_write_b16_d16_hi v80, v41 offset:896
	ds_write_b16 v80, v24 offset:192
	ds_write_b16_d16_hi v80, v24 offset:448
	ds_write_b16 v80, v25 offset:704
	ds_write_b16_d16_hi v80, v25 offset:960
	ds_read_b128 v[8:11], v81
	ds_read_b128 v[56:59], v81 offset:1024
	v_mul_f32_e32 v12, v12, v76
	v_mul_f32_e32 v13, v13, v77
	v_mul_f32_e32 v14, v14, v78
	v_mul_f32_e32 v15, v15, v79
	v_mul_f32_e32 v60, v60, v76
	v_mul_f32_e32 v61, v61, v77
	v_mul_f32_e32 v62, v62, v78
	v_mul_f32_e32 v63, v63, v79
	v_mul_f32_e32 v44, v44, v76
	v_mul_f32_e32 v45, v45, v77
	v_mul_f32_e32 v46, v46, v78
	v_mul_f32_e32 v47, v47, v79
	v_mul_f32_e32 v28, v28, v76
	v_mul_f32_e32 v29, v29, v77
	v_mul_f32_e32 v30, v30, v78
	v_mul_f32_e32 v31, v31, v79
	v_cvt_pk_bf16_f32 v12, v12, v13
	v_cvt_pk_bf16_f32 v13, v14, v15
	v_cvt_pk_bf16_f32 v60, v60, v61
	v_cvt_pk_bf16_f32 v61, v62, v63
	v_cvt_pk_bf16_f32 v44, v44, v45
	v_cvt_pk_bf16_f32 v45, v46, v47
	v_cvt_pk_bf16_f32 v28, v28, v29
	v_cvt_pk_bf16_f32 v29, v30, v31
	s_waitcnt lgkmcnt(0)
	global_store_dwordx4 v96, v[8:11], s[2:3]
	global_store_dwordx4 v96, v[56:59], s[4:5]
	s_add_u32 s2, s2, 0x4000
	s_addc_u32 s3, s3, 0
	s_add_u32 s4, s4, 0x4000
	s_addc_u32 s5, s5, 0
	ds_write_b16 v80, v12
	ds_write_b16_d16_hi v80, v12 offset:256
	ds_write_b16 v80, v13 offset:512
	ds_write_b16_d16_hi v80, v13 offset:768
	ds_write_b16 v80, v60 offset:64
	ds_write_b16_d16_hi v80, v60 offset:320
	ds_write_b16 v80, v61 offset:576
	ds_write_b16_d16_hi v80, v61 offset:832
	ds_write_b16 v80, v44 offset:128
	ds_write_b16_d16_hi v80, v44 offset:384
	ds_write_b16 v80, v45 offset:640
	ds_write_b16_d16_hi v80, v45 offset:896
	ds_write_b16 v80, v28 offset:192
	ds_write_b16_d16_hi v80, v28 offset:448
	ds_write_b16 v80, v29 offset:704
	ds_write_b16_d16_hi v80, v29 offset:960
	ds_read_b128 v[12:15], v81
	ds_read_b128 v[60:63], v81 offset:1024
	s_waitcnt lgkmcnt(0)
	global_store_dwordx4 v96, v[12:15], s[2:3]
	global_store_dwordx4 v96, v[60:63], s[4:5]
	s_add_i32 s34, s34, s10
	s_cmpk_lt_i32 s34, 0x200
	s_waitcnt vmcnt(63) expcnt(7) lgkmcnt(15)
	s_barrier
	s_cbranch_scc0 .LBB0_509
